# MoBA epilogue issues the z gate loads before the row-sum reduction and divisions
# speedup vs baseline: 1.0027x; 1.0007x over previous
.Lmb_iter_end:
	v_xor_b32_e32 v128, 65536, v128
	v_xor_b32_e32 v129, 65536, v129
	v_xor_b32_e32 v130, 65536, v130
	v_xor_b32_e32 v131, 65536, v131
	s_add_u32 s23, s23, 1
	s_waitcnt lgkmcnt(0)
	s_barrier
	s_cmp_lt_u32 s23, s22
	s_cbranch_scc1 .Lmb_loop
	v_and_b32_e32 v140, 15, v230
	s_lshl_b32 s30, s7, 5
	v_add_u32_e32 v140, s30, v140
	v_lshrrev_b32_e32 v141, 4, v230
	v_lshlrev_b32_e32 v141, 3, v141
	v_and_b32_e32 v142, 15, v230
	v_lshl_add_u32 v142, v142, 8, v141
	s_lshl_b32 s31, s7, 14
	v_add_u32_e32 v142, s31, v142
	v_lshl_add_u32 v143, v140, 12, v141
	s_add_u32 s28, s24, 25165824
	s_addc_u32 s29, s25, 0
	global_load_dwordx2 v[96:97], v142, s[28:29] offset:0
	global_load_dwordx2 v[98:99], v142, s[28:29] offset:32
	global_load_dwordx2 v[100:101], v142, s[28:29] offset:64
	global_load_dwordx2 v[102:103], v142, s[28:29] offset:96
	global_load_dwordx2 v[104:105], v142, s[28:29] offset:128
	global_load_dwordx2 v[106:107], v142, s[28:29] offset:160
	global_load_dwordx2 v[108:109], v142, s[28:29] offset:192
	global_load_dwordx2 v[110:111], v142, s[28:29] offset:224
	s_add_u32 s28, s24, 25169920
	s_addc_u32 s29, s25, 0
	global_load_dwordx2 v[112:113], v142, s[28:29] offset:0
	global_load_dwordx2 v[114:115], v142, s[28:29] offset:32
	global_load_dwordx2 v[116:117], v142, s[28:29] offset:64
	global_load_dwordx2 v[118:119], v142, s[28:29] offset:96
	global_load_dwordx2 v[120:121], v142, s[28:29] offset:128
	global_load_dwordx2 v[122:123], v142, s[28:29] offset:160
	global_load_dwordx2 v[124:125], v142, s[28:29] offset:192
	global_load_dwordx2 v[126:127], v142, s[28:29] offset:224
	s_nop 7
	ds_bpermute_b32 v158, v228, v150
	ds_bpermute_b32 v159, v228, v151
	s_waitcnt lgkmcnt(0)
	v_add_f32_e32 v150, v150, v158
	v_add_f32_e32 v151, v151, v159
	ds_bpermute_b32 v158, v229, v150
	ds_bpermute_b32 v159, v229, v151
	s_waitcnt lgkmcnt(0)
	v_add_f32_e32 v150, v150, v158
	v_add_f32_e32 v151, v151, v159
	v_div_scale_f32 v162, s[78:79], v150, v150, 1.0
	v_rcp_f32_e32 v163, v162
	v_div_scale_f32 v192, vcc, 1.0, v150, 1.0
	v_fma_f32 v193, -v162, v163, 1.0
	v_fmac_f32_e32 v163, v193, v163
	v_mul_f32_e32 v193, v192, v163
	v_fma_f32 v195, -v162, v193, v192
	v_fmac_f32_e32 v193, v195, v163
	v_fma_f32 v162, -v162, v193, v192
	v_div_fmas_f32 v162, v162, v163, v193
	v_div_fixup_f32 v160, v162, v150, 1.0
	v_div_scale_f32 v162, s[78:79], v151, v151, 1.0
	v_rcp_f32_e32 v163, v162
	v_div_scale_f32 v192, vcc, 1.0, v151, 1.0
	v_fma_f32 v193, -v162, v163, 1.0
	v_fmac_f32_e32 v163, v193, v163
	v_mul_f32_e32 v193, v192, v163
	v_fma_f32 v195, -v162, v193, v192
	v_fmac_f32_e32 v193, v195, v163
	v_fma_f32 v162, -v162, v193, v192
	v_div_fmas_f32 v162, v162, v163, v193
	v_div_fixup_f32 v161, v162, v151, 1.0
	s_lshl_b32 s30, s15, 20
	s_add_u32 s26, s10, s30
	s_addc_u32 s27, s11, 0
	s_waitcnt vmcnt(15)
	v_mul_f32_e32 v162, v0, v160
	v_mul_f32_e32 v163, v1, v160
	v_mul_f32_e32 v192, v2, v160
	v_mul_f32_e32 v193, v3, v160
	v_lshlrev_b32_e32 v195, 16, v96
	v_and_b32_e32 v203, 0xffff0000, v96
	v_mul_f32_e32 v162, v162, v195
	v_mul_f32_e32 v163, v163, v203
	v_lshlrev_b32_e32 v195, 16, v97
	v_and_b32_e32 v203, 0xffff0000, v97
	v_mul_f32_e32 v192, v192, v195
	v_mul_f32_e32 v193, v193, v203
	v_cvt_pk_bf16_f32 v96, v162, v163
	v_cvt_pk_bf16_f32 v97, v192, v193
	global_store_dwordx2 v143, v[96:97], s[26:27] offset:0
	s_waitcnt vmcnt(15)
	v_mul_f32_e32 v162, v4, v160
	v_mul_f32_e32 v163, v5, v160
	v_mul_f32_e32 v192, v6, v160
	v_mul_f32_e32 v193, v7, v160
	v_lshlrev_b32_e32 v195, 16, v98
	v_and_b32_e32 v203, 0xffff0000, v98
	v_mul_f32_e32 v162, v162, v195
	v_mul_f32_e32 v163, v163, v203
	v_lshlrev_b32_e32 v195, 16, v99
	v_and_b32_e32 v203, 0xffff0000, v99
	v_mul_f32_e32 v192, v192, v195
	v_mul_f32_e32 v193, v193, v203
	v_cvt_pk_bf16_f32 v98, v162, v163
	v_cvt_pk_bf16_f32 v99, v192, v193
	global_store_dwordx2 v143, v[98:99], s[26:27] offset:32
	s_waitcnt vmcnt(15)
	v_mul_f32_e32 v162, v8, v160
	v_mul_f32_e32 v163, v9, v160
	v_mul_f32_e32 v192, v10, v160
	v_mul_f32_e32 v193, v11, v160
	v_lshlrev_b32_e32 v195, 16, v100
	v_and_b32_e32 v203, 0xffff0000, v100
	v_mul_f32_e32 v162, v162, v195
	v_mul_f32_e32 v163, v163, v203
	v_lshlrev_b32_e32 v195, 16, v101
	v_and_b32_e32 v203, 0xffff0000, v101
	v_mul_f32_e32 v192, v192, v195
	v_mul_f32_e32 v193, v193, v203
	v_cvt_pk_bf16_f32 v100, v162, v163
	v_cvt_pk_bf16_f32 v101, v192, v193
	global_store_dwordx2 v143, v[100:101], s[26:27] offset:64
	s_waitcnt vmcnt(15)
	v_mul_f32_e32 v162, v12, v160
	v_mul_f32_e32 v163, v13, v160
	v_mul_f32_e32 v192, v14, v160
	v_mul_f32_e32 v193, v15, v160
	v_lshlrev_b32_e32 v195, 16, v102
	v_and_b32_e32 v203, 0xffff0000, v102
	v_mul_f32_e32 v162, v162, v195
	v_mul_f32_e32 v163, v163, v203
	v_lshlrev_b32_e32 v195, 16, v103
	v_and_b32_e32 v203, 0xffff0000, v103
	v_mul_f32_e32 v192, v192, v195
	v_mul_f32_e32 v193, v193, v203
	v_cvt_pk_bf16_f32 v102, v162, v163
	v_cvt_pk_bf16_f32 v103, v192, v193
	global_store_dwordx2 v143, v[102:103], s[26:27] offset:96
	s_waitcnt vmcnt(15)
	v_mul_f32_e32 v162, v16, v160
	v_mul_f32_e32 v163, v17, v160
	v_mul_f32_e32 v192, v18, v160
	v_mul_f32_e32 v193, v19, v160
	v_lshlrev_b32_e32 v195, 16, v104
	v_and_b32_e32 v203, 0xffff0000, v104
	v_mul_f32_e32 v162, v162, v195
	v_mul_f32_e32 v163, v163, v203
	v_lshlrev_b32_e32 v195, 16, v105
	v_and_b32_e32 v203, 0xffff0000, v105
	v_mul_f32_e32 v192, v192, v195
	v_mul_f32_e32 v193, v193, v203
	v_cvt_pk_bf16_f32 v104, v162, v163
	v_cvt_pk_bf16_f32 v105, v192, v193
	global_store_dwordx2 v143, v[104:105], s[26:27] offset:128
	s_waitcnt vmcnt(15)
	v_mul_f32_e32 v162, v20, v160
	v_mul_f32_e32 v163, v21, v160
	v_mul_f32_e32 v192, v22, v160
	v_mul_f32_e32 v193, v23, v160
	v_lshlrev_b32_e32 v195, 16, v106
	v_and_b32_e32 v203, 0xffff0000, v106
	v_mul_f32_e32 v162, v162, v195
	v_mul_f32_e32 v163, v163, v203
	v_lshlrev_b32_e32 v195, 16, v107
	v_and_b32_e32 v203, 0xffff0000, v107
	v_mul_f32_e32 v192, v192, v195
	v_mul_f32_e32 v193, v193, v203
	v_cvt_pk_bf16_f32 v106, v162, v163
	v_cvt_pk_bf16_f32 v107, v192, v193
	global_store_dwordx2 v143, v[106:107], s[26:27] offset:160
	s_waitcnt vmcnt(15)
	v_mul_f32_e32 v162, v24, v160
	v_mul_f32_e32 v163, v25, v160
	v_mul_f32_e32 v192, v26, v160
	v_mul_f32_e32 v193, v27, v160
	v_lshlrev_b32_e32 v195, 16, v108
	v_and_b32_e32 v203, 0xffff0000, v108
	v_mul_f32_e32 v162, v162, v195
	v_mul_f32_e32 v163, v163, v203
	v_lshlrev_b32_e32 v195, 16, v109
	v_and_b32_e32 v203, 0xffff0000, v109
	v_mul_f32_e32 v192, v192, v195
	v_mul_f32_e32 v193, v193, v203
	v_cvt_pk_bf16_f32 v108, v162, v163
	v_cvt_pk_bf16_f32 v109, v192, v193
	global_store_dwordx2 v143, v[108:109], s[26:27] offset:192
	s_waitcnt vmcnt(15)
	v_mul_f32_e32 v162, v28, v160
	v_mul_f32_e32 v163, v29, v160
	v_mul_f32_e32 v192, v30, v160
	v_mul_f32_e32 v193, v31, v160
	v_lshlrev_b32_e32 v195, 16, v110
	v_and_b32_e32 v203, 0xffff0000, v110
	v_mul_f32_e32 v162, v162, v195
	v_mul_f32_e32 v163, v163, v203
	v_lshlrev_b32_e32 v195, 16, v111
	v_and_b32_e32 v203, 0xffff0000, v111
	v_mul_f32_e32 v192, v192, v195
	v_mul_f32_e32 v193, v193, v203
	v_cvt_pk_bf16_f32 v110, v162, v163
	v_cvt_pk_bf16_f32 v111, v192, v193
	global_store_dwordx2 v143, v[110:111], s[26:27] offset:224
	s_add_u32 s26, s26, 0x10000
	s_addc_u32 s27, s27, 0
	s_waitcnt vmcnt(15)
	v_mul_f32_e32 v162, v32, v161
	v_mul_f32_e32 v163, v33, v161
	v_mul_f32_e32 v192, v34, v161
	v_mul_f32_e32 v193, v35, v161
	v_lshlrev_b32_e32 v195, 16, v112
	v_and_b32_e32 v203, 0xffff0000, v112
	v_mul_f32_e32 v162, v162, v195
	v_mul_f32_e32 v163, v163, v203
	v_lshlrev_b32_e32 v195, 16, v113
	v_and_b32_e32 v203, 0xffff0000, v113
	v_mul_f32_e32 v192, v192, v195
	v_mul_f32_e32 v193, v193, v203
	v_cvt_pk_bf16_f32 v112, v162, v163
	v_cvt_pk_bf16_f32 v113, v192, v193
	global_store_dwordx2 v143, v[112:113], s[26:27] offset:0
	s_waitcnt vmcnt(15)
	v_mul_f32_e32 v162, v36, v161
	v_mul_f32_e32 v163, v37, v161
	v_mul_f32_e32 v192, v38, v161
	v_mul_f32_e32 v193, v39, v161
	v_lshlrev_b32_e32 v195, 16, v114
	v_and_b32_e32 v203, 0xffff0000, v114
	v_mul_f32_e32 v162, v162, v195
	v_mul_f32_e32 v163, v163, v203
	v_lshlrev_b32_e32 v195, 16, v115
	v_and_b32_e32 v203, 0xffff0000, v115
	v_mul_f32_e32 v192, v192, v195
	v_mul_f32_e32 v193, v193, v203
	v_cvt_pk_bf16_f32 v114, v162, v163
	v_cvt_pk_bf16_f32 v115, v192, v193
	global_store_dwordx2 v143, v[114:115], s[26:27] offset:32
	s_waitcnt vmcnt(15)
	v_mul_f32_e32 v162, v40, v161
	v_mul_f32_e32 v163, v41, v161
	v_mul_f32_e32 v192, v42, v161
	v_mul_f32_e32 v193, v43, v161
	v_lshlrev_b32_e32 v195, 16, v116
	v_and_b32_e32 v203, 0xffff0000, v116
	v_mul_f32_e32 v162, v162, v195
	v_mul_f32_e32 v163, v163, v203
	v_lshlrev_b32_e32 v195, 16, v117
	v_and_b32_e32 v203, 0xffff0000, v117
	v_mul_f32_e32 v192, v192, v195
	v_mul_f32_e32 v193, v193, v203
	v_cvt_pk_bf16_f32 v116, v162, v163
	v_cvt_pk_bf16_f32 v117, v192, v193
	global_store_dwordx2 v143, v[116:117], s[26:27] offset:64
	s_waitcnt vmcnt(15)
	v_mul_f32_e32 v162, v44, v161
	v_mul_f32_e32 v163, v45, v161
	v_mul_f32_e32 v192, v46, v161
	v_mul_f32_e32 v193, v47, v161
	v_lshlrev_b32_e32 v195, 16, v118
	v_and_b32_e32 v203, 0xffff0000, v118
	v_mul_f32_e32 v162, v162, v195
	v_mul_f32_e32 v163, v163, v203
	v_lshlrev_b32_e32 v195, 16, v119
	v_and_b32_e32 v203, 0xffff0000, v119
	v_mul_f32_e32 v192, v192, v195
	v_mul_f32_e32 v193, v193, v203
	v_cvt_pk_bf16_f32 v118, v162, v163
	v_cvt_pk_bf16_f32 v119, v192, v193
	global_store_dwordx2 v143, v[118:119], s[26:27] offset:96
	s_waitcnt vmcnt(15)
	v_mul_f32_e32 v162, v48, v161
	v_mul_f32_e32 v163, v49, v161
	v_mul_f32_e32 v192, v50, v161
	v_mul_f32_e32 v193, v51, v161
	v_lshlrev_b32_e32 v195, 16, v120
	v_and_b32_e32 v203, 0xffff0000, v120
	v_mul_f32_e32 v162, v162, v195
	v_mul_f32_e32 v163, v163, v203
	v_lshlrev_b32_e32 v195, 16, v121
	v_and_b32_e32 v203, 0xffff0000, v121
	v_mul_f32_e32 v192, v192, v195
	v_mul_f32_e32 v193, v193, v203
	v_cvt_pk_bf16_f32 v120, v162, v163
	v_cvt_pk_bf16_f32 v121, v192, v193
	global_store_dwordx2 v143, v[120:121], s[26:27] offset:128
	s_waitcnt vmcnt(15)
	v_mul_f32_e32 v162, v52, v161
	v_mul_f32_e32 v163, v53, v161
	v_mul_f32_e32 v192, v54, v161
	v_mul_f32_e32 v193, v55, v161
	v_lshlrev_b32_e32 v195, 16, v122
	v_and_b32_e32 v203, 0xffff0000, v122
	v_mul_f32_e32 v162, v162, v195
	v_mul_f32_e32 v163, v163, v203
	v_lshlrev_b32_e32 v195, 16, v123
	v_and_b32_e32 v203, 0xffff0000, v123
	v_mul_f32_e32 v192, v192, v195
	v_mul_f32_e32 v193, v193, v203
	v_cvt_pk_bf16_f32 v122, v162, v163
	v_cvt_pk_bf16_f32 v123, v192, v193
	global_store_dwordx2 v143, v[122:123], s[26:27] offset:160
	s_waitcnt vmcnt(15)
	v_mul_f32_e32 v162, v56, v161
	v_mul_f32_e32 v163, v57, v161
	v_mul_f32_e32 v192, v58, v161
	v_mul_f32_e32 v193, v59, v161
	v_lshlrev_b32_e32 v195, 16, v124
	v_and_b32_e32 v203, 0xffff0000, v124
	v_mul_f32_e32 v162, v162, v195
	v_mul_f32_e32 v163, v163, v203
	v_lshlrev_b32_e32 v195, 16, v125
	v_and_b32_e32 v203, 0xffff0000, v125
	v_mul_f32_e32 v192, v192, v195
	v_mul_f32_e32 v193, v193, v203
	v_cvt_pk_bf16_f32 v124, v162, v163
	v_cvt_pk_bf16_f32 v125, v192, v193
	global_store_dwordx2 v143, v[124:125], s[26:27] offset:192
	s_waitcnt vmcnt(15)
	v_mul_f32_e32 v162, v60, v161
	v_mul_f32_e32 v163, v61, v161
	v_mul_f32_e32 v192, v62, v161
	v_mul_f32_e32 v193, v63, v161
	v_lshlrev_b32_e32 v195, 16, v126
	v_and_b32_e32 v203, 0xffff0000, v126
	v_mul_f32_e32 v162, v162, v195
	v_mul_f32_e32 v163, v163, v203
	v_lshlrev_b32_e32 v195, 16, v127
	v_and_b32_e32 v203, 0xffff0000, v127
	v_mul_f32_e32 v192, v192, v195
	v_mul_f32_e32 v193, v193, v203
	v_cvt_pk_bf16_f32 v126, v162, v163
	v_cvt_pk_bf16_f32 v127, v192, v193
	global_store_dwordx2 v143, v[126:127], s[26:27] offset:224
	s_add_u32 s14, s14, 1
	s_cmp_lt_u32 s14, 2
	s_cbranch_scc1 .Lmb_task
	s_setprio 0
	s_cmpk_lt_i32 s96, 0x800
	s_cselect_b64 s[10:11], -1, 0
	s_cmpk_gt_i32 s96, 0x7ff
	v_lshlrev_b32_e32 v156, 4, v198
	v_cmp_gt_u32_e64 s[8:9], 64, v198
	s_waitcnt lgkmcnt(0)
	s_barrier
	s_cbranch_scc1 .LBB0_356
	s_ashr_i32 s2, s96, 8
	s_lshl_b32 s0, s96, 6
	s_ashr_i32 s3, s2, 31
	s_and_b32 s0, s0, 0x7c0
	s_lshl_b64 s[2:3], s[2:3], 11
	s_ashr_i32 s12, s96, 5
	s_or_b32 s1, s2, s0
	s_add_u32 s4, s1, -3
	v_mov_b32_e32 v129, 0
	s_addc_u32 s5, s3, 0x3ffff
	v_or_b32_e32 v6, s0, v136
	v_mov_b32_e32 v137, v129
	v_lshl_add_u64 v[2:3], s[4:5], 0, v[136:137]
	v_mov_b32_e32 v7, s3
	v_cmp_lt_u32_e64 s[2:3], 2, v6
	v_mov_b32_e32 v8, s1
	v_add_u32_e32 v0, 0x200, v198
	v_cndmask_b32_e64 v5, v7, v3, s[2:3]
	v_cndmask_b32_e64 v4, v8, v2, s[2:3]
	v_lshlrev_b64 v[4:5], 14, v[4:5]
	s_lshl_b32 s1, s12, 8
	v_lshrrev_b32_e32 v128, 4, v0
	s_mov_b32 s15, 0
	v_lshl_add_u64 v[4:5], s[66:67], 0, v[4:5]
	s_and_b32 s14, s1, 0x700
	v_lshl_add_u64 v[0:1], s[4:5], 0, v[128:129]
	v_lshl_add_u64 v[4:5], v[4:5], 0, s[14:15]
	v_and_b32_e32 v128, 0xf0, v156
	v_lshl_add_u64 v[16:17], v[4:5], 0, v[128:129]
	v_lshl_add_u64 v[4:5], v[2:3], 0, 1
	v_cmp_lt_u32_e64 s[4:5], 1, v6
	v_cmp_eq_u32_e64 s[6:7], 0, v6
	s_mov_b32 s1, 0xc000
	v_cndmask_b32_e64 v5, v7, v5, s[4:5]
	v_cndmask_b32_e64 v4, v8, v4, s[4:5]
	v_lshlrev_b64 v[4:5], 14, v[4:5]
	v_lshl_add_u64 v[4:5], s[66:67], 0, v[4:5]
	v_lshl_add_u64 v[4:5], v[4:5], 0, s[14:15]
	v_lshl_add_u64 v[18:19], v[4:5], 0, v[128:129]
	v_lshl_add_u64 v[4:5], v[2:3], 0, 2
	v_cndmask_b32_e64 v5, v5, v7, s[6:7]
	v_cndmask_b32_e64 v4, v4, v8, s[6:7]
	v_lshlrev_b64 v[2:3], 14, v[2:3]
	v_lshlrev_b64 v[4:5], 14, v[4:5]
	v_lshl_add_u64 v[2:3], s[66:67], 0, v[2:3]
	v_lshl_add_u64 v[4:5], s[66:67], 0, v[4:5]
	v_lshl_add_u64 v[2:3], v[2:3], 0, s[14:15]
	v_lshl_add_u64 v[4:5], v[4:5], 0, s[14:15]
	v_lshl_add_u64 v[2:3], v[2:3], 0, v[128:129]
	v_lshl_add_u64 v[44:45], v[4:5], 0, v[128:129]
	v_add_co_u32_e32 v4, vcc, s1, v2
	v_lshlrev_b64 v[0:1], 14, v[0:1]
	s_nop 0
	v_addc_co_u32_e32 v5, vcc, 0, v3, vcc
	s_mov_b32 s13, 0xd000
	v_lshl_add_u64 v[0:1], s[66:67], 0, v[0:1]
	v_add_co_u32_e32 v46, vcc, s13, v2
	v_lshl_add_u64 v[0:1], v[0:1], 0, s[14:15]
	s_nop 0
	v_addc_co_u32_e32 v47, vcc, 0, v3, vcc
	v_lshl_add_u64 v[48:49], v[0:1], 0, v[128:129]
	s_movk_i32 s13, 0x4000
	v_add_co_u32_e32 v12, vcc, s13, v48
	s_mov_b32 s13, 0x8000
	s_nop 0
	v_addc_co_u32_e32 v13, vcc, 0, v49, vcc
	v_add_co_u32_e32 v32, vcc, s13, v48
	v_mov_b32_e32 v135, v129
	s_nop 0
	v_addc_co_u32_e32 v33, vcc, 0, v49, vcc
	v_add_co_u32_e32 v36, vcc, s1, v48
	s_movk_i32 s1, 0x1000
	s_nop 0
	v_addc_co_u32_e32 v37, vcc, 0, v49, vcc
	global_load_dwordx4 v[40:43], v[16:17], off
	global_load_dwordx4 v[80:83], v[16:17], off offset:2048
	global_load_dwordx4 v[94:97], v[18:19], off
	global_load_dwordx4 v[76:79], v[18:19], off offset:2048
	global_load_dwordx4 v[62:65], v[44:45], off
	global_load_dwordx4 v[86:89], v[44:45], off offset:2048
	global_load_dwordx4 v[0:3], v[48:49], off
	global_load_dwordx4 v[20:23], v[4:5], off offset:2048
	s_nop 0
	global_load_dwordx4 v[4:7], v[12:13], off
	global_load_dwordx4 v[24:27], v[48:49], off offset:2048
	global_load_dwordx4 v[8:11], v[32:33], off
	global_load_dwordx4 v[28:31], v[12:13], off offset:2048
	s_nop 0
	global_load_dwordx4 v[12:15], v[36:37], off
	s_nop 0
	global_load_dwordx4 v[32:35], v[32:33], off offset:2048
	v_add_co_u32_e32 v16, vcc, s1, v16
	s_nop 1
	v_addc_co_u32_e32 v17, vcc, 0, v17, vcc
	global_load_dwordx4 v[36:39], v[36:37], off offset:2048
	s_nop 0
	global_load_dwordx4 v[90:93], v[16:17], off
	v_add_co_u32_e32 v16, vcc, s1, v18
	s_nop 1
	v_addc_co_u32_e32 v17, vcc, 0, v19, vcc
	v_add_co_u32_e32 v18, vcc, s1, v44
	s_nop 1
	v_addc_co_u32_e32 v19, vcc, 0, v45, vcc
	v_add_co_u32_e32 v50, vcc, s1, v48
	global_load_dwordx4 v[102:105], v[16:17], off
	global_load_dwordx4 v[98:101], v[18:19], off
	s_nop 0
	global_load_dwordx4 v[16:19], v[46:47], off offset:-4096
	s_nop 0
	global_load_dwordx4 v[44:47], v[46:47], off
	v_addc_co_u32_e32 v51, vcc, 0, v49, vcc
	v_add_co_u32_e32 v56, vcc, 0x5000, v48
	s_nop 1
	v_addc_co_u32_e32 v57, vcc, 0, v49, vcc
	global_load_dwordx4 v[52:55], v[50:51], off
	global_load_dwordx4 v[58:61], v[56:57], off
	v_add_co_u32_e32 v50, vcc, 0x9000, v48
	s_nop 1
	v_addc_co_u32_e32 v51, vcc, 0, v49, vcc
	v_add_co_u32_e32 v48, vcc, 0xd000, v48
	s_nop 1
	v_addc_co_u32_e32 v49, vcc, 0, v49, vcc
	global_load_dwordx4 v[66:69], v[50:51], off
	global_load_dwordx4 v[72:75], v[48:49], off
	s_and_saveexec_b64 s[14:15], s[8:9]
	s_cbranch_execz .LBB0_355
	s_ashr_i32 s13, s12, 31
	v_or_b32_e32 v48, s0, v198
	v_mov_b32_e32 v49, 0
	v_lshlrev_b64 v[48:49], 2, v[48:49]
	s_lshl_b64 s[0:1], s[12:13], 13
	v_or_b32_e32 v49, s1, v49
	v_or_b32_e32 v48, s0, v48
	v_lshl_add_u64 v[50:51], s[72:73], 0, v[48:49]
	v_lshl_add_u64 v[48:49], s[74:75], 0, v[48:49]
	global_load_dword v129, v[48:49], off
	global_load_dword v135, v[50:51], off
